# attention wave priorities flipped: the younger half (waves 4-7) runs at the higher priority (3) and waves 0-3 at 2
# baseline (speedup 1.0000x reference)
; __device__ __forceinline__ void attn_phase(int wv, const bf16_t* Q, const bf16_t* Kf, const bf16_t* Vt, const bf16_t* proj, bf16_t* mixed, LAS unsigned char* lds) { LIDS
;     ...
;     if (wid >= 4) __builtin_amdgcn_s_setprio(1);
;     ...
;             for (int t = 0; t < nt; ++t) {
;                 const int b = t & 1;
;                 asm volatile("s_waitcnt vmcnt(0)" ::: "memory"); __builtin_amdgcn_s_barrier(); asm volatile("" ::: "memory");
.Lp2_loop0:
	s_waitcnt vmcnt(0)
	s_barrier
	s_setprio 2
	s_cmp_lt_u32 s3, 4
	s_cbranch_scc1 .Lp2_pr
	s_setprio 3
